# grid barrier: the 16th arriver of each XCD issues one early L2 write-back so the leader's write-back on the critical path finds less dirty data
# speedup vs baseline: 1.0036x; 1.0008x over previous
.LBB0_140:
	s_or_b64 exec, exec, s[8:9]
	v_cvt_f32_u32_e32 v4, v2
	s_waitcnt vmcnt(0)
	v_readfirstlane_b32 s3, v3
	v_sub_u32_e32 v3, 0, v2
	v_rcp_iflag_f32_e32 v4, v4
	v_add_u32_e32 v5, s3, v1
	v_mul_f32_e32 v4, 0x4f7ffffe, v4
	v_cvt_u32_f32_e32 v4, v4
	v_mul_lo_u32 v1, v3, v4
	v_mul_hi_u32 v1, v4, v1
	v_add_u32_e32 v1, v4, v1
	v_mul_hi_u32 v1, v5, v1
	v_mul_lo_u32 v3, v1, v2
	v_sub_u32_e32 v3, v5, v3
	v_add_u32_e32 v4, 1, v1
	v_cmp_ge_u32_e32 vcc, v3, v2
	s_nop 1
	v_cndmask_b32_e32 v1, v1, v4, vcc
	v_sub_u32_e32 v4, v3, v2
	v_cndmask_b32_e32 v3, v3, v4, vcc
	v_add_u32_e32 v4, 1, v1
	v_cmp_ge_u32_e32 vcc, v3, v2
	v_add_u32_e32 v3, 1, v5
	s_nop 0
	v_cndmask_b32_e32 v1, v1, v4, vcc
	v_mul_lo_u32 v4, v2, v1
	v_add_u32_e32 v2, v4, v2
	v_cmp_ne_u32_e32 vcc, v3, v2
	s_and_saveexec_b64 s[6:7], vcc
	s_xor_b64 s[6:7], exec, s[6:7]
	s_cbranch_execz .LBB0_154
	s_waitcnt lgkmcnt(0)
	v_mov_b32_e32 v0, 0x2000
	buffer_inv sc1
	v_readfirstlane_b32 s12, v5
	s_and_b32 s12, s12, 31
	s_cmp_eq_u32 s12, 16
	s_cbranch_scc0 .Lewb_skip1
	buffer_wbl2 sc1
.Lewb_skip1:
	global_load_dword v0, v0, s[4:5] offset:1024 sc1
	s_add_u32 s12, s4, 0x2400
	s_addc_u32 s13, s5, 0
	s_waitcnt vmcnt(0)
	v_cmp_eq_u32_e32 vcc, v0, v1
	s_and_saveexec_b64 s[8:9], vcc
	s_cbranch_execz .LBB0_153
	s_add_u32 s10, s24, 0x28100200
	s_addc_u32 s11, s25, 0
	s_mov_b32 s3, 1
	s_mov_b64 s[14:15], 0
	v_mov_b32_e32 v0, 0
	s_branch .LBB0_144

.LBB0_939:
	s_or_b64 exec, exec, s[16:17]
	v_cvt_f32_u32_e32 v4, v2
	s_waitcnt vmcnt(0)
	v_readfirstlane_b32 s2, v3
	v_sub_u32_e32 v3, 0, v2
	v_rcp_iflag_f32_e32 v4, v4
	v_add_u32_e32 v5, s2, v1
	v_mul_f32_e32 v4, 0x4f7ffffe, v4
	v_cvt_u32_f32_e32 v4, v4
	v_mul_lo_u32 v1, v3, v4
	v_mul_hi_u32 v1, v4, v1
	v_add_u32_e32 v1, v4, v1
	v_mul_hi_u32 v1, v5, v1
	v_mul_lo_u32 v3, v1, v2
	v_sub_u32_e32 v3, v5, v3
	v_add_u32_e32 v4, 1, v1
	v_cmp_ge_u32_e32 vcc, v3, v2
	s_nop 1
	v_cndmask_b32_e32 v1, v1, v4, vcc
	v_sub_u32_e32 v4, v3, v2
	v_cndmask_b32_e32 v3, v3, v4, vcc
	v_add_u32_e32 v4, 1, v1
	v_cmp_ge_u32_e32 vcc, v3, v2
	v_add_u32_e32 v3, 1, v5
	s_nop 0
	v_cndmask_b32_e32 v1, v1, v4, vcc
	v_mul_lo_u32 v4, v2, v1
	v_add_u32_e32 v2, v4, v2
	v_cmp_ne_u32_e32 vcc, v3, v2
	s_and_saveexec_b64 s[8:9], vcc
	s_xor_b64 s[14:15], exec, s[8:9]
	s_cbranch_execz .LBB0_953
	s_waitcnt lgkmcnt(0)
	buffer_inv sc1
	v_readfirstlane_b32 s18, v5
	s_and_b32 s18, s18, 31
	s_cmp_eq_u32 s18, 16
	s_cbranch_scc0 .Lewb_skip2
	buffer_wbl2 sc1
.Lewb_skip2:
	global_load_dword v0, v223, s[12:13] offset:1024 sc1
	s_add_u32 s18, s12, 0x2400
	s_addc_u32 s19, s13, 0
	s_waitcnt vmcnt(0)
	v_cmp_eq_u32_e32 vcc, v0, v1
	s_and_saveexec_b64 s[16:17], vcc
	s_cbranch_execz .LBB0_952
	s_mov_b32 s2, 1
	s_mov_b64 s[20:21], 0
	s_branch .LBB0_943

.LBB0_1593:
	s_or_b64 exec, exec, s[18:19]
	v_cvt_f32_u32_e32 v4, v2
	s_waitcnt vmcnt(0)
	v_readfirstlane_b32 s2, v3
	v_sub_u32_e32 v3, 0, v2
	v_rcp_iflag_f32_e32 v4, v4
	v_add_u32_e32 v5, s2, v1
	v_mul_f32_e32 v4, 0x4f7ffffe, v4
	v_cvt_u32_f32_e32 v4, v4
	v_mul_lo_u32 v1, v3, v4
	v_mul_hi_u32 v1, v4, v1
	v_add_u32_e32 v1, v4, v1
	v_mul_hi_u32 v1, v5, v1
	v_mul_lo_u32 v3, v1, v2
	v_sub_u32_e32 v3, v5, v3
	v_add_u32_e32 v4, 1, v1
	v_cmp_ge_u32_e32 vcc, v3, v2
	s_nop 1
	v_cndmask_b32_e32 v1, v1, v4, vcc
	v_sub_u32_e32 v4, v3, v2
	v_cndmask_b32_e32 v3, v3, v4, vcc
	v_add_u32_e32 v4, 1, v1
	v_cmp_ge_u32_e32 vcc, v3, v2
	v_add_u32_e32 v3, 1, v5
	s_nop 0
	v_cndmask_b32_e32 v1, v1, v4, vcc
	v_mul_lo_u32 v4, v2, v1
	v_add_u32_e32 v2, v4, v2
	v_cmp_ne_u32_e32 vcc, v3, v2
	s_and_saveexec_b64 s[8:9], vcc
	s_xor_b64 s[16:17], exec, s[8:9]
	s_cbranch_execz .LBB0_1607
	s_waitcnt lgkmcnt(0)
	buffer_inv sc1
	v_readfirstlane_b32 s20, v5
	s_and_b32 s20, s20, 31
	s_cmp_eq_u32 s20, 16
	s_cbranch_scc0 .Lewb_skip5
	buffer_wbl2 sc1
.Lewb_skip5:
	global_load_dword v0, v223, s[14:15] offset:1024 sc1
	s_add_u32 s20, s14, 0x2400
	s_addc_u32 s21, s15, 0
	s_waitcnt vmcnt(0)
	v_cmp_eq_u32_e32 vcc, v0, v1
	s_and_saveexec_b64 s[18:19], vcc
	s_cbranch_execz .LBB0_1606
	s_mov_b32 s2, 1
	s_mov_b64 s[30:31], 0
	s_branch .LBB0_1597

.LBB0_1713:
	s_or_b64 exec, exec, s[16:17]
	v_cvt_f32_u32_e32 v4, v2
	s_waitcnt vmcnt(0)
	v_readfirstlane_b32 s8, v3
	v_sub_u32_e32 v3, 0, v2
	v_rcp_iflag_f32_e32 v4, v4
	v_add_u32_e32 v5, s8, v1
	v_mul_f32_e32 v4, 0x4f7ffffe, v4
	v_cvt_u32_f32_e32 v4, v4
	v_mul_lo_u32 v1, v3, v4
	v_mul_hi_u32 v1, v4, v1
	v_add_u32_e32 v1, v4, v1
	v_mul_hi_u32 v1, v5, v1
	v_mul_lo_u32 v3, v1, v2
	v_sub_u32_e32 v3, v5, v3
	v_add_u32_e32 v4, 1, v1
	v_cmp_ge_u32_e32 vcc, v3, v2
	s_nop 1
	v_cndmask_b32_e32 v1, v1, v4, vcc
	v_sub_u32_e32 v4, v3, v2
	v_cndmask_b32_e32 v3, v3, v4, vcc
	v_add_u32_e32 v4, 1, v1
	v_cmp_ge_u32_e32 vcc, v3, v2
	v_add_u32_e32 v3, 1, v5
	s_nop 0
	v_cndmask_b32_e32 v1, v1, v4, vcc
	v_mul_lo_u32 v4, v2, v1
	v_add_u32_e32 v2, v4, v2
	v_cmp_ne_u32_e32 vcc, v3, v2
	s_and_saveexec_b64 s[8:9], vcc
	s_xor_b64 s[14:15], exec, s[8:9]
	s_cbranch_execz .LBB0_1727
	s_waitcnt lgkmcnt(0)
	buffer_inv sc1
	v_readfirstlane_b32 s18, v5
	s_and_b32 s18, s18, 31
	s_cmp_eq_u32 s18, 16
	s_cbranch_scc0 .Lewb_skip6
	buffer_wbl2 sc1
.Lewb_skip6:
	global_load_dword v0, v223, s[12:13] offset:1024 sc1
	s_add_u32 s18, s12, 0x2400
	s_addc_u32 s19, s13, 0
	s_waitcnt vmcnt(0)
	v_cmp_eq_u32_e32 vcc, v0, v1
	s_and_saveexec_b64 s[16:17], vcc
	s_cbranch_execz .LBB0_1726
	s_mov_b32 s8, 1
	s_mov_b64 s[20:21], 0
	s_branch .LBB0_1717
